# in-projection epilogue: non-temporal hint on the projection-buffer stores (keeps the normalized input resident for the later N tiles)
# speedup vs baseline: 1.0067x; 1.0003x over previous
.LBB0_221:
	v_lshl_or_b32 v154, s81, 8, v150
	v_ashrrev_i32_e32 v155, 31, v154
	v_mov_b64_e32 v[156:157], s[8:9]
	v_cvt_pk_bf16_f32 v68, v68, v69
	v_cvt_pk_bf16_f32 v69, v70, v71
	v_cvt_pk_bf16_f32 v70, v64, v65
	v_add_u32_e32 v64, 0x80, v146
	v_mad_i64_i32 v[158:159], s[28:29], v146, s80, v[156:157]
	v_lshlrev_b64 v[154:155], 1, v[154:155]
	v_cvt_pk_bf16_f32 v108, v108, v109
	v_cvt_pk_bf16_f32 v109, v110, v111
	v_cvt_pk_bf16_f32 v110, v104, v105
	v_or_b32_e32 v104, 16, v146
	v_mad_i64_i32 v[64:65], s[28:29], v64, s80, v[156:157]
	v_cvt_pk_bf16_f32 v44, v44, v45
	v_cvt_pk_bf16_f32 v45, v46, v47
	v_cvt_pk_bf16_f32 v46, v40, v41
	v_add_u32_e32 v40, 0x90, v146
	v_lshl_add_u64 v[158:159], v[158:159], 0, v[154:155]
	v_cvt_pk_bf16_f32 v111, v106, v107
	v_mad_i64_i32 v[104:105], s[28:29], v104, s80, v[156:157]
	v_cvt_pk_bf16_f32 v92, v92, v93
	v_cvt_pk_bf16_f32 v93, v94, v95
	v_cvt_pk_bf16_f32 v94, v88, v89
	v_or_b32_e32 v88, 32, v146
	v_lshl_add_u64 v[64:65], v[64:65], 0, v[154:155]
	v_cvt_pk_bf16_f32 v47, v42, v43
	v_mad_i64_i32 v[40:41], s[28:29], v40, s80, v[156:157]
	v_cvt_pk_bf16_f32 v28, v28, v29
	v_cvt_pk_bf16_f32 v29, v30, v31
	v_cvt_pk_bf16_f32 v30, v24, v25
	v_add_u32_e32 v24, 0xa0, v146
	global_store_dwordx4 v[158:159], v[108:111], off offset:256 nt
	v_cvt_pk_bf16_f32 v95, v90, v91
	v_mad_i64_i32 v[88:89], s[28:29], v88, s80, v[156:157]
	v_lshl_add_u64 v[108:109], v[104:105], 0, v[154:155]
	v_cvt_pk_bf16_f32 v76, v76, v77
	v_cvt_pk_bf16_f32 v77, v78, v79
	v_cvt_pk_bf16_f32 v78, v72, v73
	v_or_b32_e32 v72, 48, v146
	global_store_dwordx4 v[64:65], v[44:47], off offset:256 nt
	v_cvt_pk_bf16_f32 v31, v26, v27
	v_mad_i64_i32 v[24:25], s[28:29], v24, s80, v[156:157]
	v_lshl_add_u64 v[44:45], v[40:41], 0, v[154:155]
	v_cvt_pk_bf16_f32 v12, v12, v13
	v_cvt_pk_bf16_f32 v13, v14, v15
	v_cvt_pk_bf16_f32 v14, v8, v9
	v_add_u32_e32 v8, 0xb0, v146
	global_store_dwordx4 v[108:109], v[92:95], off offset:256 nt
	v_cvt_pk_bf16_f32 v79, v74, v75
	v_mad_i64_i32 v[72:73], s[28:29], v72, s80, v[156:157]
	v_lshl_add_u64 v[92:93], v[88:89], 0, v[154:155]
	global_store_dwordx4 v[44:45], v[28:31], off offset:256 nt
	v_cvt_pk_bf16_f32 v15, v10, v11
	v_mad_i64_i32 v[8:9], s[28:29], v8, s80, v[156:157]
	v_lshl_add_u64 v[28:29], v[24:25], 0, v[154:155]
	v_cvt_pk_bf16_f32 v124, v124, v125
	v_cvt_pk_bf16_f32 v125, v126, v127
	v_cvt_pk_bf16_f32 v126, v120, v121
	v_cvt_pk_bf16_f32 v127, v122, v123
	v_cvt_pk_bf16_f32 v104, v116, v117
	v_cvt_pk_bf16_f32 v105, v118, v119
	v_cvt_pk_bf16_f32 v106, v112, v113
	v_cvt_pk_bf16_f32 v107, v114, v115
	v_cvt_pk_bf16_f32 v88, v100, v101
	v_cvt_pk_bf16_f32 v89, v102, v103
	v_cvt_pk_bf16_f32 v90, v96, v97
	v_cvt_pk_bf16_f32 v91, v98, v99
	global_store_dwordx4 v[92:93], v[76:79], off offset:256 nt
	v_cvt_pk_bf16_f32 v74, v80, v81
	v_cvt_pk_bf16_f32 v75, v82, v83
	v_lshl_add_u64 v[76:77], v[72:73], 0, v[154:155]
	v_cvt_pk_bf16_f32 v72, v84, v85
	v_cvt_pk_bf16_f32 v73, v86, v87
	v_cvt_pk_bf16_f32 v71, v66, v67
	v_cvt_pk_bf16_f32 v60, v60, v61
	v_cvt_pk_bf16_f32 v61, v62, v63
	v_cvt_pk_bf16_f32 v62, v56, v57
	v_cvt_pk_bf16_f32 v63, v58, v59
	v_cvt_pk_bf16_f32 v40, v52, v53
	v_cvt_pk_bf16_f32 v41, v54, v55
	v_cvt_pk_bf16_f32 v42, v48, v49
	v_cvt_pk_bf16_f32 v43, v50, v51
	v_cvt_pk_bf16_f32 v24, v36, v37
	v_cvt_pk_bf16_f32 v25, v38, v39
	v_cvt_pk_bf16_f32 v26, v32, v33
	v_cvt_pk_bf16_f32 v27, v34, v35
	global_store_dwordx4 v[28:29], v[12:15], off offset:256 nt
	v_cvt_pk_bf16_f32 v10, v16, v17
	v_cvt_pk_bf16_f32 v11, v18, v19
	v_lshl_add_u64 v[12:13], v[8:9], 0, v[154:155]
	v_cvt_pk_bf16_f32 v8, v20, v21
	v_cvt_pk_bf16_f32 v9, v22, v23
	v_cvt_pk_bf16_f32 v4, v4, v5
	v_cvt_pk_bf16_f32 v5, v6, v7
	v_cvt_pk_bf16_f32 v6, v0, v1
	v_cvt_pk_bf16_f32 v7, v2, v3
	global_store_dwordx4 v[158:159], v[124:127], off nt
	global_store_dwordx4 v[108:109], v[104:107], off nt
	global_store_dwordx4 v[92:93], v[88:91], off nt
	global_store_dwordx4 v[76:77], v[72:75], off nt
	global_store_dwordx4 v[76:77], v[68:71], off offset:256 nt
	global_store_dwordx4 v[64:65], v[60:63], off nt
	global_store_dwordx4 v[44:45], v[40:43], off nt
	global_store_dwordx4 v[28:29], v[24:27], off nt
	global_store_dwordx4 v[12:13], v[8:11], off nt
	global_store_dwordx4 v[12:13], v[4:7], off offset:256 nt
	s_andn2_b64 vcc, exec, s[2:3]
	s_mov_b64 s[2:3], -1
	s_cbranch_vccnz .LBB0_209
	s_branch .LBB0_226

.LBB0_228:
	v_or_b32_e32 v156, 16, v146
	v_ashrrev_i32_e32 v147, 31, v146
	v_ashrrev_i32_e32 v157, 31, v156
	v_lshlrev_b64 v[154:155], 7, v[146:147]
	v_lshlrev_b64 v[156:157], 7, v[156:157]
	v_lshl_add_u64 v[154:155], v[136:137], 0, v[154:155]
	v_lshl_add_u64 v[156:157], v[136:137], 0, v[156:157]
	global_store_dwordx4 v[154:155], v[124:127], off nt
	global_store_dwordx4 v[154:155], v[120:123], off offset:16 nt
	global_store_dwordx4 v[156:157], v[116:119], off nt
	global_store_dwordx4 v[156:157], v[112:115], off offset:16 nt
	v_or_b32_e32 v156, 32, v146
	v_ashrrev_i32_e32 v157, 31, v156
	v_lshlrev_b64 v[156:157], 7, v[156:157]
	v_lshl_add_u64 v[156:157], v[136:137], 0, v[156:157]
	global_store_dwordx4 v[156:157], v[100:103], off nt
	global_store_dwordx4 v[156:157], v[96:99], off offset:16 nt
	v_or_b32_e32 v156, 48, v146
	v_ashrrev_i32_e32 v157, 31, v156
	v_lshlrev_b64 v[156:157], 7, v[156:157]
	v_lshl_add_u64 v[156:157], v[136:137], 0, v[156:157]
	v_add_co_u32_e32 v158, vcc, s53, v154
	global_store_dwordx4 v[156:157], v[84:87], off nt
	global_store_dwordx4 v[156:157], v[80:83], off offset:16 nt
	v_lshl_add_u64 v[156:157], v[154:155], 0, s[16:17]
	v_addc_co_u32_e32 v159, vcc, 0, v155, vcc
	global_store_dwordx4 v[158:159], v[60:63], off nt
	global_store_dwordx4 v[156:157], v[56:59], off offset:16 nt
	v_lshl_add_u64 v[156:157], v[154:155], 0, s[18:19]
	global_store_dwordx4 v[158:159], v[52:55], off offset:2048 nt
	global_store_dwordx4 v[156:157], v[48:51], off offset:16 nt
	v_add_co_u32_e32 v158, vcc, 0x5000, v154
	v_lshl_add_u64 v[156:157], v[154:155], 0, s[20:21]
	s_nop 0
	v_addc_co_u32_e32 v159, vcc, 0, v155, vcc
	global_store_dwordx4 v[158:159], v[36:39], off nt
	global_store_dwordx4 v[156:157], v[32:35], off offset:16 nt
	v_lshl_add_u64 v[154:155], v[154:155], 0, s[22:23]
	global_store_dwordx4 v[158:159], v[20:23], off offset:2048 nt
	global_store_dwordx4 v[154:155], v[16:19], off offset:16 nt
	s_cbranch_execnz .LBB0_225
	s_branch .LBB0_221
